# v64 + one static s_setprio 1 for the second-slot workgroup of each CU at the start of the three mixer phases (strategy lever 4)
# baseline (speedup 1.0000x reference)
.LBB0_326:
	s_or_b64 exec, exec, s[0:1]
	s_lshl_b32 s22, s84, 6
	s_mov_b64 s[0:1], -1
	s_and_b64 vcc, exec, s[8:9]
	s_waitcnt lgkmcnt(0)
	s_barrier
	s_sleep 32
	s_cbranch_vccz .LBB0_500
	v_readlane_b32 s0, v254, 29
	v_readlane_b32 s1, v254, 30
	s_and_b64 vcc, exec, s[0:1]
	s_cbranch_vccz .LBB0_329
	s_sleep 0x7f
	s_setprio 1

.LBB0_500:
	s_and_b64 vcc, exec, s[0:1]
	s_cbranch_vccz .LBB0_798
	v_readlane_b32 s0, v254, 29
	v_readlane_b32 s1, v254, 30
	s_and_b64 vcc, exec, s[0:1]
	s_cbranch_vccz .LBB0_503
	s_sleep 0x7f
	s_setprio 1

.LBB0_603:
	s_or_b64 exec, exec, s[0:1]
	v_readlane_b32 s0, v254, 29
	v_readlane_b32 s1, v254, 30
	s_andn2_b64 vcc, exec, s[0:1]
	s_waitcnt lgkmcnt(0)
	s_barrier
	s_sleep 32
	s_cbranch_vccnz .LBB0_605
	s_sleep 0x7f
	s_setprio 1
